# full stack: v031 + attention softmax tail in PV gaps + attention K tile key-major swizzled (coalesced DMA) + cross 3-slot ring + K-rope epilogue prefetch with relaxed waits
# speedup vs baseline: 1.0125x; 1.0020x over previous
; #define LAS __attribute__((address_space(3)))
; DI int crow(int i, int hh) { return (i & 3) + 8 * (i >> 2) + 4 * hh; }
; #define LOADV(f, ks) _Pragma("unroll") for (int nb = 0; nb < 4; ++nb) { const s16x4 lo = vtr(vp + nb * 4096 + (ks) * 1024), hi = vtr(vp + nb * 4096 + (ks) * 1024 + 512); f[nb] = __builtin_shufflevector(lo, hi, 0, 1, 2, 3, 4, 5, 6, 7); }
; #define SB __builtin_amdgcn_sched_barrier(0);
; #define GRP(P, i, f, ks, nb) { ls += qa_ + qb_; float ea_, eb_; asm volatile("v_exp_f32 %0, %2\n\tv_exp_f32 %1, %3" : "=&v"(ea_), "=&v"(eb_) : "v"(P[i]), "v"(P[(i) + 1])); P[i] = ea_; P[(i) + 1] = eb_; qa_ = ea_; qb_ = eb_; \
;                   o[nb] = __builtin_amdgcn_mfma_f32_32x32x16_bf16(pfc[ks], f[nb], o[nb], 0, 0, 0); SB }
; DI void attn_unit(Ctx A_, LAS unsigned char* lds, int b, int h, int qb, float lam, int wave, int lane) {
;     ...
;               SB __builtin_amdgcn_s_setprio(1); SB
;               GRP(p0, 0, fa4, 0, 0) GRP(p0, 2, fa4, 0, 1) GRP(p0, 4, fa4, 0, 2) GRP(p0, 6, fa4, 0, 3)
;               LOADV(fa4, 2) SB
;               pfn[0] = pack8(p0, 0);
;               GRP(p0, 8, fb4, 1, 0) GRP(p0, 10, fb4, 1, 1) GRP(p0, 12, fb4, 1, 2) GRP(p0, 14, fb4, 1, 3)
;               LOADV(fb4, 3) SB
;               { const LAS unsigned char* kn = lds + ((t + 1) & 3) * BUF + (mp * 8 + hh) * 1024 + r * 16;
; #pragma unroll
;                 for (int d0 = 0; d0 < 2; ++d0) { kfa[2 * d0] = *(const LAS bf16x8*)(kn + d0 * 2048); kfa[2 * d0 + 1] = *(const LAS bf16x8*)(kn + d0 * 2048 + 512); } }
;               SB
;               pfn[1] = pack8(p0, 8);
;               GRP(p1, 0, fa4, 2, 0) GRP(p1, 2, fa4, 2, 1) GRP(p1, 4, fa4, 2, 2) GRP(p1, 6, fa4, 2, 3)
;               pfn[2] = pack8(p1, 0);
;               GRP(p1, 8, fb4, 3, 0) GRP(p1, 10, fb4, 3, 1) GRP(p1, 12, fb4, 3, 2) GRP(p1, 14, fb4, 3, 3)
;               __builtin_amdgcn_s_setprio(0); SB
;               ls += qa_ + qb_; pfn[3] = pack8(p1, 8);
;     ...
;             }
;             l += ls;
; #pragma unroll
;             for (int i = 0; i < 4; ++i) pfc[i] = pfn[i];
;             if (resc) {
;                 float fr[16];
; #pragma unroll
;                 for (int i = 0; i < 16; ++i) fr[i] = wsf[crow(i, hh)];
; #pragma unroll
;                 for (int nb = 0; nb < 4; ++nb)
; #pragma unroll
;                     for (int i = 0; i < 16; ++i) o[nb][i] *= fr[i];
.LBB0_886:
	s_setprio 1
	v_mfma_f32_32x32x16_bf16 v[34:49], v[190:193], v[134:137], v[34:49]
	v_exp_f32 v221, v98
	v_exp_f32 v222, v99
	v_lshl_add_u64 v[198:199], v[198:199], 0, s[18:19]
	s_waitcnt lgkmcnt(10)
	v_mfma_f32_32x32x16_bf16 v[50:65], v[190:193], v[142:145], v[50:65]
	v_exp_f32 v134, v100
	v_exp_f32 v135, v101
	v_add_f32_e32 v240, v221, v222
	v_lshl_add_u64 v[200:201], v[200:201], 0, s[18:19]
	s_waitcnt lgkmcnt(6)
	v_mfma_f32_32x32x16_bf16 v[18:33], v[190:193], v[138:141], v[18:33]
	v_exp_f32 v136, v102
	v_exp_f32 v137, v103
	v_add_f32_e32 v241, v134, v135
	v_add_f32_e32 v240, 0, v240
	s_waitcnt lgkmcnt(2)
	v_mfma_f32_32x32x16_bf16 v[2:17], v[190:193], v[130:133], v[2:17]
	v_exp_f32 v138, v104
	v_exp_f32 v139, v105
	v_add_f32_e32 v242, v136, v137
	v_add_f32_e32 v243, v240, v241
	ds_read_b64_tr_b16 v[130:131], v220 offset:18432
	ds_read_b64_tr_b16 v[132:133], v220 offset:18944
	ds_read_b64_tr_b16 v[140:141], v220 offset:22528
	ds_read_b64_tr_b16 v[142:143], v220 offset:23040
	ds_read_b64_tr_b16 v[190:191], v220 offset:26624
	ds_read_b64_tr_b16 v[192:193], v220 offset:27136
	ds_read_b64_tr_b16 v[224:225], v220 offset:30720
	ds_read_b64_tr_b16 v[226:227], v220 offset:31232
	v_mfma_f32_32x32x16_bf16 v[34:49], v[170:173], v[126:129], v[34:49]
	v_exp_f32 v100, v106
	v_exp_f32 v98, v107
	v_add_f32_e32 v244, v138, v139
	v_add_f32_e32 v242, v243, v242
	v_mfma_f32_32x32x16_bf16 v[50:65], v[170:173], v[122:125], v[50:65]
	v_exp_f32 v101, v108
	v_exp_f32 v99, v109
	v_add_f32_e32 v242, v242, v244
	v_lshl_add_u64 v[202:203], v[202:203], 0, s[18:19]
	v_mfma_f32_32x32x16_bf16 v[18:33], v[170:173], v[118:121], v[18:33]
	v_exp_f32 v104, v110
	v_exp_f32 v102, v111
	v_pk_add_f32 v[240:241], v[100:101], v[98:99]
	v_add_f32_e32 v240, v242, v240
	s_waitcnt lgkmcnt(8)
	v_mfma_f32_32x32x16_bf16 v[2:17], v[170:173], v[114:117], v[2:17]
	v_exp_f32 v105, v112
	v_exp_f32 v103, v113
	v_add_f32_e32 v242, v240, v241
	v_cvt_pk_bf16_f32 v170, v100, v98
	v_cvt_pk_bf16_f32 v171, v101, v99
	ds_read_b64_tr_b16 v[114:115], v220 offset:19456
	ds_read_b64_tr_b16 v[116:117], v220 offset:19968
	ds_read_b64_tr_b16 v[118:119], v220 offset:23552
	ds_read_b64_tr_b16 v[120:121], v220 offset:24064
	ds_read_b64_tr_b16 v[122:123], v220 offset:27648
	ds_read_b64_tr_b16 v[124:125], v220 offset:28160
	ds_read_b64_tr_b16 v[126:127], v220 offset:31744
	ds_read_b64_tr_b16 v[128:129], v220 offset:32256
	s_add_i32 s4, s66, 0x8000
	s_and_b32 s4, s4, 0x18000
	v_add_u32_e32 v106, s4, v216
	v_xor_b32_e32 v107, 32, v106
	ds_read_b128 v[174:177], v106
	ds_read_b128 v[178:181], v106 offset:8192
	ds_read_b128 v[182:185], v107
	ds_read_b128 v[186:189], v107 offset:8192
	s_waitcnt lgkmcnt(14)
	v_mfma_f32_32x32x16_bf16 v[34:49], v[166:169], v[130:133], v[34:49]
	v_exp_f32 v108, v82
	v_exp_f32 v106, v83
	v_pk_add_f32 v[240:241], v[104:105], v[102:103]
	v_add_f32_e32 v240, v242, v240
	v_cvt_pk_bf16_f32 v172, v104, v102
	v_mfma_f32_32x32x16_bf16 v[50:65], v[166:169], v[140:143], v[50:65]
	v_exp_f32 v109, v84
	v_exp_f32 v107, v85
	v_add_f32_e32 v250, v240, v241
	v_cvt_pk_bf16_f32 v173, v105, v103
	v_mfma_f32_32x32x16_bf16 v[18:33], v[166:169], v[190:193], v[18:33]
	v_exp_f32 v112, v86
	v_exp_f32 v110, v87
	v_pk_add_f32 v[242:243], v[108:109], v[106:107]
	v_cvt_pk_bf16_f32 v190, v221, v222
	s_waitcnt lgkmcnt(12)
	v_mfma_f32_32x32x16_bf16 v[2:17], v[166:169], v[224:227], v[2:17]
	v_exp_f32 v113, v88
	v_exp_f32 v111, v89
	v_add_f32_e32 v250, v250, v242
	v_cvt_pk_bf16_f32 v191, v134, v135
	v_cvt_pk_bf16_f32 v166, v108, v106
	s_waitcnt lgkmcnt(10)
	v_mfma_f32_32x32x16_bf16 v[34:49], v[162:165], v[114:117], v[34:49]
	v_exp_f32 v84, v90
	v_exp_f32 v82, v91
	v_pk_add_f32 v[244:245], v[112:113], v[110:111]
	v_add_f32_e32 v250, v250, v243
	v_cvt_pk_bf16_f32 v192, v136, v137
	s_waitcnt lgkmcnt(8)
	v_mfma_f32_32x32x16_bf16 v[50:65], v[162:165], v[118:121], v[50:65]
	v_exp_f32 v85, v92
	v_exp_f32 v83, v93
	v_add_f32_e32 v250, v250, v244
	v_add_f32_e32 v250, v250, v245
	v_cvt_pk_bf16_f32 v193, v138, v139
	s_waitcnt lgkmcnt(6)
	v_mfma_f32_32x32x16_bf16 v[18:33], v[162:165], v[122:125], v[18:33]
	v_exp_f32 v88, v94
	v_exp_f32 v86, v95
	v_pk_add_f32 v[246:247], v[84:85], v[82:83]
	v_cvt_pk_bf16_f32 v167, v109, v107
	v_cvt_pk_bf16_f32 v168, v112, v110
	s_waitcnt lgkmcnt(4)
	v_mfma_f32_32x32x16_bf16 v[2:17], v[162:165], v[126:129], v[2:17]
	v_exp_f32 v89, v96
	v_exp_f32 v87, v97
	v_add_f32_e32 v250, v250, v246
	v_cvt_pk_bf16_f32 v169, v113, v111
	v_cvt_pk_bf16_f32 v162, v84, v82
	v_cvt_pk_bf16_f32 v163, v85, v83
	s_setprio 0
	s_and_b64 vcc, exec, s[6:7]
	s_cbranch_vccnz .LBB0_888
	v_add_u32_e32 v118, s40, v194
	ds_read_b128 v[90:93], v118 offset:96
	ds_read_b128 v[94:97], v118 offset:64
	ds_read_b128 v[114:117], v118 offset:32
	ds_read_b128 v[118:121], v118
	s_waitcnt lgkmcnt(3)
	v_pk_mul_f32 v[46:47], v[46:47], v[90:91]
	s_waitcnt lgkmcnt(2)
	v_pk_mul_f32 v[42:43], v[42:43], v[94:95]
	s_waitcnt lgkmcnt(1)
	v_pk_mul_f32 v[38:39], v[38:39], v[114:115]
	v_pk_mul_f32 v[48:49], v[48:49], v[92:93]
	v_pk_mul_f32 v[44:45], v[44:45], v[96:97]
	v_pk_mul_f32 v[40:41], v[40:41], v[116:117]
	s_waitcnt lgkmcnt(0)
	v_pk_mul_f32 v[36:37], v[36:37], v[120:121]
	v_pk_mul_f32 v[34:35], v[34:35], v[118:119]
	v_pk_mul_f32 v[62:63], v[62:63], v[90:91]
	v_pk_mul_f32 v[58:59], v[58:59], v[94:95]
	v_pk_mul_f32 v[54:55], v[54:55], v[114:115]
	v_pk_mul_f32 v[64:65], v[64:65], v[92:93]
	v_pk_mul_f32 v[60:61], v[60:61], v[96:97]
	v_pk_mul_f32 v[56:57], v[56:57], v[116:117]
	v_pk_mul_f32 v[52:53], v[52:53], v[120:121]
	v_pk_mul_f32 v[50:51], v[50:51], v[118:119]
	v_pk_mul_f32 v[30:31], v[30:31], v[90:91]
	v_pk_mul_f32 v[26:27], v[26:27], v[94:95]
	v_pk_mul_f32 v[22:23], v[22:23], v[114:115]
	v_pk_mul_f32 v[32:33], v[32:33], v[92:93]
	v_pk_mul_f32 v[28:29], v[28:29], v[96:97]
	v_pk_mul_f32 v[24:25], v[24:25], v[116:117]
	v_pk_mul_f32 v[20:21], v[20:21], v[120:121]
	v_pk_mul_f32 v[18:19], v[18:19], v[118:119]
	v_pk_mul_f32 v[14:15], v[14:15], v[90:91]
	v_pk_mul_f32 v[10:11], v[10:11], v[94:95]
	v_pk_mul_f32 v[6:7], v[6:7], v[114:115]
	v_pk_mul_f32 v[16:17], v[16:17], v[92:93]
	v_pk_mul_f32 v[12:13], v[12:13], v[96:97]
	v_pk_mul_f32 v[8:9], v[8:9], v[116:117]
	v_pk_mul_f32 v[4:5], v[4:5], v[120:121]
	v_pk_mul_f32 v[2:3], v[2:3], v[118:119]
